# K-tile-1 staging loads issued together with K-tile-0's at the start of every multi-unit GEMM phase (G3/G1 before the table, G2/G4 before the first wait)
# speedup vs baseline: 1.0111x; 1.0023x over previous
.LBB0_141:
	s_andn2_b64 vcc, exec, s[4:5]
	s_cbranch_vccnz .LBB0_352
	v_readlane_b32 s2, v254, 36
	s_add_u32 s30, s2, s16
	v_readlane_b32 s2, v254, 39
	v_ashrrev_i32_e32 v2, 6, v170
	s_addc_u32 s31, s2, s17
	v_cmp_gt_i32_e32 vcc, 8, v2
	s_and_saveexec_b64 s[38:39], vcc
	v_readlane_b32 s0, v254, 40
	s_mov_b64 s[80:81], 0x200
	v_readlane_b32 s1, v254, 41
	s_cmp_gt_i32 s22, 63
	s_cselect_b64 s[98:99], -1, 0
	s_and_b64 s[98:99], s[98:99], s[0:1]
	s_and_b64 vcc, exec, s[98:99]
	s_cbranch_vccnz .Lhoist_g3a_skip
	v_readlane_b32 s84, v254, 31
	v_readlane_b32 s82, v254, 37
	v_readlane_b32 s83, v254, 38
	s_mul_i32 s84, s84, 0xb00000
	s_add_u32 s84, s82, s84
	s_addc_u32 s85, s83, 0
	s_add_u32 s84, s84, 0x2100000
	s_addc_u32 s85, s85, 0
	s_mov_b32 s76, s72
	s_ashr_i32 s77, s72, 31
	s_lshl_b64 s[76:77], s[76:77], 19
	s_add_u32 s84, s84, s76
	s_addc_u32 s85, s85, s77
	s_mov_b32 s76, s22
	s_ashr_i32 s77, s22, 31
	s_lshl_b64 s[76:77], s[76:77], 19
	s_add_u32 s82, s48, s76
	s_addc_u32 s83, s49, s77
	s_ashr_i32 s86, s29, 6
	s_lshl_b32 s86, s86, 10
	s_add_i32 m0, s86, 0x10000
	s_nop 0
	global_load_lds_dwordx4 v164, s[84:85]
	s_add_i32 m0, s86, 0x12000
	s_nop 0
	global_load_lds_dwordx4 v174, s[84:85]
	s_add_u32 s76, s84, 0x40000
	s_addc_u32 s77, s85, 0
	s_add_i32 m0, s86, 0x14000
	s_nop 0
	global_load_lds_dwordx4 v164, s[76:77]
	s_add_i32 m0, s86, 0x16000
	s_nop 0
	global_load_lds_dwordx4 v174, s[76:77]
	s_mov_b32 m0, s86
	s_nop 0
	global_load_lds_dwordx4 v162, s[82:83]
	s_add_i32 m0, s86, 0x2000
	s_nop 0
	global_load_lds_dwordx4 v172, s[82:83]
	s_add_u32 s76, s82, 0x40000
	s_addc_u32 s77, s83, 0
	s_add_i32 m0, s86, 0x4000
	s_nop 0
	global_load_lds_dwordx4 v162, s[76:77]
	s_add_i32 m0, s86, 0x6000
	s_nop 0
	global_load_lds_dwordx4 v172, s[76:77]
	s_add_u32 s96, s84, 0x80
	s_addc_u32 s97, s85, 0
	s_add_i32 m0, s86, 0x18000
	s_nop 0
	global_load_lds_dwordx4 v164, s[96:97]
	s_add_i32 m0, s86, 0x1a000
	s_nop 0
	global_load_lds_dwordx4 v174, s[96:97]
	s_add_u32 s96, s82, 0x80
	s_addc_u32 s97, s83, 0
	s_add_i32 m0, s86, 0x8000
	s_nop 0
	global_load_lds_dwordx4 v162, s[96:97]
	s_add_i32 m0, s86, 0xa000
	s_nop 0
	global_load_lds_dwordx4 v172, s[96:97]
	s_add_u32 s96, s84, 0x40080
	s_addc_u32 s97, s85, 0
	s_add_i32 m0, s86, 0x1c000
	s_nop 0
	global_load_lds_dwordx4 v164, s[96:97]
	s_add_i32 m0, s86, 0x1e000
	s_nop 0
	global_load_lds_dwordx4 v174, s[96:97]

.LBB0_243:
	s_lshl_b32 s4, s34, 2
	v_readlane_b32 s40, v254, 37
	v_readlane_b32 s41, v254, 38
	s_add_u32 s4, s40, s4
	s_addc_u32 s5, s41, 0
	s_add_u32 s89, s4, 0x18000
	s_addc_u32 s90, s5, 0
	s_add_u32 s52, s40, 0xf600000
	v_lshrrev_b32_e32 v0, 1, v170
	s_addc_u32 s53, s41, 0
	v_and_b32_e32 v0, 24, v0
	s_lshl_b32 s2, s2, 5
	v_lshlrev_b32_e32 v10, 6, v189
	v_lshlrev_b32_e32 v11, 1, v0
	s_movk_i32 s4, 0x3c0
	s_and_b32 s34, s2, 0x60
	s_add_i32 m0, s21, 0x18000
	v_lshl_add_u64 v[8:9], v[8:9], 0, s[14:15]
	v_lshl_or_b32 v171, s3, 6, v189
	v_and_or_b32 v10, v10, s4, v11
	s_lshl_b32 s3, s3, 13
	v_lshlrev_b32_e32 v12, 2, v189
	v_or_b32_e32 v11, v11, v188
	s_lshl_b32 s2, s34, 7
	s_waitcnt vmcnt(2)
	s_barrier
	s_cbranch_vccz .Lhoist_g3c5
	global_load_lds_dwordx4 v[8:9], off
.Lhoist_g3c5:
	v_lshl_add_u64 v[6:7], v[6:7], 0, s[14:15]
	s_add_i32 m0, s21, 0x1a000
	s_add_i32 s91, s21, 0x8000
	s_add_i32 s92, s21, 0xa000
	v_and_b32_e32 v13, 32, v12
	v_bitop3_b32 v188, s2, v11, v190 bitop3:0xf6
	s_cbranch_vccz .Lhoist_g3c4
	global_load_lds_dwordx4 v[6:7], off
.Lhoist_g3c4:
	v_lshl_add_u64 v[2:3], v[2:3], 0, s[14:15]
	s_mov_b32 m0, s91
	s_add_u32 s2, s74, 0x40080
	v_bitop3_b32 v10, v10, s3, v13 bitop3:0xde
	s_cbranch_vccz .Lhoist_g3c3
	global_load_lds_dwordx4 v[2:3], off
.Lhoist_g3c3:
	v_lshl_add_u64 v[2:3], v[4:5], 0, s[14:15]
	s_mov_b32 m0, s92
	s_addc_u32 s3, s75, 0
	s_cbranch_vccz .Lhoist_g3c2
	global_load_lds_dwordx4 v[2:3], off
.Lhoist_g3c2:
	s_add_i32 m0, s21, 0x1c000
	v_lshl_add_u64 v[2:3], s[2:3], 0, v[164:165]
	s_cbranch_vccz .Lhoist_g3c1
	global_load_lds_dwordx4 v[2:3], off
.Lhoist_g3c1:
	s_add_i32 m0, s21, 0x1e000
	s_cmpk_lt_u32 s29, 0x100
	v_lshl_add_u64 v[2:3], s[2:3], 0, v[174:175]
	s_cselect_b64 s[54:55], -1, 0
	s_and_b32 s2, s29, 0xffffff00
	s_add_i32 s2, s2, 0
	s_lshr_b32 s95, s10, 3
	s_cbranch_vccz .Lhoist_g3c0
	global_load_lds_dwordx4 v[2:3], off
.Lhoist_g3c0:
	s_add_i32 s2, s2, 0x20800
	s_ashr_i32 s93, s94, 31
	s_mov_b32 s42, s94
	s_and_b32 s40, s10, 4
	s_add_i32 s96, s95, 1
	v_mov_b32_e32 v2, 0x98
	s_cmpk_gt_i32 s94, 0x7f
	v_sub_co_u32_e32 v4, vcc, s42, v2
	s_cselect_b64 s[58:59], -1, 0
	s_xor_b64 s[60:61], vcc, -1
	s_cmpk_gt_u32 s94, 0xc3
	v_add_u32_e32 v189, s2, v12
	s_cselect_b64 s[2:3], -1, 0
	v_writelane_b32 v255, s2, 29
	s_cmpk_gt_u32 s94, 0xf7
	s_mov_b32 s11, s17
	v_writelane_b32 v255, s3, 30
	s_cselect_b64 s[2:3], -1, 0
	v_writelane_b32 v255, s2, 31
	s_cmpk_lt_u32 s94, 0xcc
	s_cselect_b64 s[62:63], -1, 0
	v_writelane_b32 v255, s3, 32
	s_cmpk_lt_u32 s94, 0xf4
	s_movk_i32 s2, 0xffd0
	s_cselect_b32 s2, s2, 0xffffffa4
	s_add_i32 s2, s2, s94
	s_add_i32 s16, s2, 0x400
	v_mov_b64_e32 v[2:3], s[10:11]
	s_and_b32 s2, s2, 7
	v_mov_b32_e32 v5, s40
	v_cmp_ge_u64_e64 s[4:5], s[16:17], v[2:3]
	v_sub_co_u32_e32 v2, vcc, s2, v5
	s_nop 0
	v_readfirstlane_b32 s3, v2
	s_mul_i32 s97, s96, s40
	s_mul_i32 s3, s3, s95
	s_lshr_b32 s29, s16, 3
	s_add_i32 s71, s97, s3
	s_mul_i32 s73, s96, s2
	s_add_i32 s2, s94, 0x134
	v_writelane_b32 v254, s4, 46
	s_cmp_lt_i32 s2, s10
	s_waitcnt vmcnt(6)
	s_mov_b32 s66, s94
	v_writelane_b32 v254, s5, 47
	s_cselect_b64 s[4:5], -1, 0
	v_writelane_b32 v254, s4, 48
	s_mov_b32 s67, s17
	v_cmp_eq_u32_e64 s[44:45], 0, v206
	v_writelane_b32 v254, s5, 49
	s_and_b32 s4, s2, 7
	v_sub_co_u32_e64 v2, s[2:3], s4, v5
	s_nop 0
	v_readfirstlane_b32 s5, v2
	s_mul_i32 s5, s5, s95
	s_add_i32 s76, s97, s5
	s_mul_i32 s77, s96, s4
	v_readfirstlane_b32 s4, v4
	s_cmp_gt_u32 s4, 21
	s_cselect_b32 s25, 0x41, 64
	s_add_i32 s4, s94, 0xffffff52
	v_mov_b32_e32 v2, s4
	v_cmp_gt_u32_e64 s[4:5], 22, v4
	v_mov_b32_e32 v192, s72
	v_mov_b64_e32 v[130:131], s[74:75]
	v_cndmask_b32_e64 v190, v2, v4, s[4:5]
	s_add_i32 s4, s94, 0xffffff80
	s_lshr_b32 s4, s4, 3
	s_add_i32 s16, s4, 2
	s_lshl_b64 s[4:5], s[16:17], 8
	s_add_u32 s4, s4, s94
	s_addc_u32 s5, s5, 0
	s_or_b32 s4, s4, 0xf8
	v_mov_b64_e32 v[2:3], s[10:11]
	v_cmp_ge_u64_e64 s[42:43], s[4:5], v[2:3]
	s_lshr_b32 s16, s4, 3
	v_sub_co_u32_e64 v2, s[4:5], s70, v5
	s_nop 0
	v_readfirstlane_b32 s41, v2
	s_mul_i32 s41, s41, s95
	s_add_i32 s78, s97, s41
	s_and_b64 s[68:69], vcc, exec
	s_cselect_b32 s68, s73, s71
	s_add_i32 s68, s68, s29
	s_mul_hi_u32 s29, s68, 0xba2e8ba3
	s_lshr_b32 s29, s29, 7
	s_lshl_b32 s69, s29, 3
	s_sub_i32 s71, 64, s69
	s_mulk_i32 s29, 0xb0
	s_min_i32 s71, s71, 8
	s_sub_i32 s29, s68, s29
	s_and_b64 s[2:3], s[2:3], exec
	s_cselect_b32 s2, s77, s76
	s_add_i32 s2, s2, 63
	s_mul_hi_u32 s3, s2, 0xba2e8ba3
	s_lshr_b32 s3, s3, 7
	s_lshl_b32 s68, s3, 3
	s_sub_i32 s73, 64, s68
	s_mulk_i32 s3, 0xb0
	s_min_i32 s73, s73, 8
	s_sub_i32 s76, s2, s3
	s_mul_i32 s70, s96, s70
	s_and_b64 s[2:3], s[4:5], exec
	s_cselect_b32 s2, s70, s78
	s_abs_i32 s4, s71
	v_cvt_f32_u32_e32 v2, s4
	s_sub_i32 s77, 0, s4
	s_add_i32 s2, s2, s16
	s_mul_hi_u32 s3, s2, 0xba2e8ba3
	v_rcp_iflag_f32_e32 v2, v2
	s_abs_i32 s70, s29
	s_lshr_b32 s3, s3, 7
	s_lshl_b32 s5, s3, 3
	v_mul_f32_e32 v2, 0x4f7ffffe, v2
	v_cvt_u32_f32_e32 v2, v2
	s_mulk_i32 s3, 0xb0
	s_sub_i32 s16, 64, s5
	s_sub_i32 s2, s2, s3
	v_readfirstlane_b32 s78, v2
	s_mul_i32 s77, s77, s78
	s_mul_hi_u32 s77, s78, s77
	s_add_i32 s78, s78, s77
	s_mul_hi_u32 s77, s70, s78
	s_mul_i32 s78, s77, s4
	s_xor_b32 s3, s29, s71
	s_sub_i32 s70, s70, s78
	s_min_i32 s16, s16, 8
	s_ashr_i32 s3, s3, 31
	s_add_i32 s78, s77, 1
	s_sub_i32 s79, s70, s4
	s_cmp_ge_u32 s70, s4
	s_cselect_b32 s77, s78, s77
	s_cselect_b32 s70, s79, s70
	s_add_i32 s78, s77, 1
	s_cmp_ge_u32 s70, s4
	s_cselect_b32 s4, s78, s77
	s_abs_i32 s77, s73
	v_cvt_f32_u32_e32 v2, s77
	s_xor_b32 s4, s4, s3
	s_sub_i32 s70, s4, s3
	s_mul_i32 s3, s70, s71
	v_rcp_iflag_f32_e32 v2, v2
	s_sub_i32 s3, s29, s3
	s_add_i32 s65, s69, s3
	s_sub_i32 s29, 0, s77
	v_mul_f32_e32 v2, 0x4f7ffffe, v2
	v_cvt_u32_f32_e32 v2, v2
	s_abs_i32 s4, s76
	s_xor_b32 s3, s76, s73
	s_ashr_i32 s3, s3, 31
	v_readfirstlane_b32 s69, v2
	s_mul_i32 s29, s29, s69
	s_mul_hi_u32 s29, s69, s29
	s_add_i32 s69, s69, s29
	s_mul_hi_u32 s29, s4, s69
	s_mul_i32 s69, s29, s77
	s_sub_i32 s4, s4, s69
	s_add_i32 s69, s29, 1
	s_sub_i32 s71, s4, s77
	s_cmp_ge_u32 s4, s77
	s_cselect_b32 s29, s69, s29
	s_cselect_b32 s4, s71, s4
	s_add_i32 s69, s29, 1
	s_cmp_ge_u32 s4, s77
	s_cselect_b32 s4, s69, s29
	s_abs_i32 s29, s16
	v_cvt_f32_u32_e32 v2, s29
	s_xor_b32 s4, s4, s3
	s_sub_i32 s71, s4, s3
	s_mul_i32 s3, s71, s73
	v_rcp_iflag_f32_e32 v2, v2
	s_sub_i32 s3, s76, s3
	s_add_i32 s3, s68, s3
	s_sub_i32 s68, 0, s29
	v_mul_f32_e32 v2, 0x4f7ffffe, v2
	v_cvt_u32_f32_e32 v2, v2
	s_abs_i32 s4, s2
	v_writelane_b32 v254, s3, 62
	s_xor_b32 s3, s2, s16
	v_readfirstlane_b32 s69, v2
	s_mul_i32 s68, s68, s69
	s_mul_hi_u32 s68, s69, s68
	s_add_i32 s69, s69, s68
	s_mul_hi_u32 s68, s4, s69
	s_mul_i32 s69, s68, s29
	s_sub_i32 s4, s4, s69
	s_ashr_i32 s3, s3, 31
	s_add_i32 s69, s68, 1
	s_sub_i32 s73, s4, s29
	s_cmp_ge_u32 s4, s29
	s_cselect_b32 s68, s69, s68
	s_cselect_b32 s4, s73, s4
	s_add_i32 s69, s68, 1
	s_cmp_ge_u32 s4, s29
	s_cselect_b32 s4, s69, s68
	s_xor_b32 s4, s4, s3
	s_sub_i32 s68, s4, s3
	s_mul_i32 s3, s68, s16
	s_sub_i32 s2, s2, s3
	v_mov_b32_e32 v2, 0
	s_mov_b32 s41, 0
	s_add_i32 s69, s5, s2
	v_add_u32_e32 v191, 0, v10
	s_lshl_b32 s4, s34, 1
	v_lshlrev_b32_e32 v0, 1, v0
	s_barrier
	s_branch .LBB0_246

.LBB0_361:
	s_andn2_b64 vcc, exec, s[10:11]
	s_cbranch_vccnz .LBB0_477
	v_bfe_i32 v3, v170, 27, 1
	v_lshlrev_b32_e32 v2, 4, v170
	v_lshrrev_b32_e32 v3, 22, v3
	v_add_u32_e32 v3, v2, v3
	v_and_b32_e32 v3, 0xfffffc00, v3
	v_sub_u32_e32 v3, v2, v3
	v_ashrrev_i32_e32 v0, 31, v170
	v_lshrrev_b32_e32 v4, 4, v3
	v_lshrrev_b32_e32 v0, 26, v0
	v_bitop3_b32 v3, v4, v3, 32 bitop3:0x6c
	v_add_u32_e32 v0, v170, v0
	v_ashrrev_i32_e32 v5, 31, v3
	v_ashrrev_i32_e32 v0, 6, v0
	v_lshrrev_b32_e32 v5, 26, v5
	v_lshlrev_b32_e32 v4, 3, v0
	v_add_u32_e32 v5, v3, v5
	v_and_b32_e32 v4, -16, v4
	v_ashrrev_i32_e32 v6, 6, v5
	v_lshlrev_b32_e32 v0, 5, v0
	v_readlane_b32 s36, v254, 37
	v_add_u32_e32 v4, v6, v4
	v_and_b32_e32 v14, 32, v0
	v_and_b32_e32 v0, 0xc0, v5
	s_add_u32 s21, s36, s6
	v_sub_u32_e32 v0, v3, v0
	v_lshlrev_b32_e32 v3, 1, v4
	v_lshrrev_b32_e32 v5, 2, v4
	v_and_b32_e32 v6, 3, v6
	s_mov_b32 s6, 0x7fffffe0
	v_ashrrev_i16_sdwa v0, v209, sext(v0) dst_sel:DWORD dst_unused:UNUSED_PAD src0_sel:DWORD src1_sel:BYTE_0
	v_and_b32_e32 v3, 24, v3
	v_and_b32_e32 v5, 4, v5
	v_and_or_b32 v6, v4, s6, v6
	v_bfe_i32 v15, v0, 0, 16
	v_or3_b32 v3, v6, v5, v3
	v_add_u32_e32 v0, v14, v15
	v_mul_lo_u32 v16, s22, v4
	v_mul_lo_u32 v3, s22, v3
	v_add_u32_e32 v2, 0x2000, v2
	s_waitcnt vmcnt(0)
	v_add_lshl_u32 v162, v16, v0, 1
	v_add_lshl_u32 v0, v3, v0, 1
	v_ashrrev_i32_e32 v3, 31, v2
	v_lshrrev_b32_e32 v3, 22, v3
	v_add_u32_e32 v3, v2, v3
	v_ashrrev_i32_e32 v3, 10, v3
	v_mul_i32_i24_e32 v4, 0x400, v3
	v_sub_u32_e32 v2, v2, v4
	v_lshrrev_b32_e32 v4, 4, v2
	v_bitop3_b32 v2, v4, v2, 32 bitop3:0x6c
	v_ashrrev_i32_e32 v5, 31, v2
	v_lshrrev_b32_e32 v5, 26, v5
	v_readlane_b32 s37, v254, 38
	v_lshlrev_b32_e32 v4, 3, v3
	v_add_u32_e32 v5, v2, v5
	s_addc_u32 s26, s37, s7
	s_ashr_i32 s30, s5, 6
	v_and_b32_e32 v4, -16, v4
	v_ashrrev_i32_e32 v6, 6, v5
	v_add_u32_e32 v4, v6, v4
	v_and_b32_e32 v6, 3, v6
	s_ashr_i32 s31, s5, 8
	s_lshl_b32 s16, s22, 8
	s_lshl_b32 s50, s22, 9
	s_lshl_b32 s51, s30, 10
	v_and_or_b32 v6, v4, s6, v6
	s_and_b64 s[6:7], s[8:9], exec
	s_mov_b32 s6, 0xf600000
	s_cselect_b32 s6, s6, 0xcc00000
	v_lshlrev_b32_e32 v3, 5, v3
	s_add_u32 s52, s36, s6
	v_and_b32_e32 v17, 32, v3
	v_and_b32_e32 v3, 0xc0, v5
	s_addc_u32 s53, s37, 0
	s_mul_i32 s7, s50, s27
	v_sub_u32_e32 v2, v2, v3
	v_lshlrev_b32_e32 v3, 1, v4
	v_lshrrev_b32_e32 v5, 2, v4
	s_mul_hi_i32 s6, s50, s27
	s_add_u32 s42, s21, s7
	v_ashrrev_i16_sdwa v2, v209, sext(v2) dst_sel:DWORD dst_unused:UNUSED_PAD src0_sel:DWORD src1_sel:BYTE_0
	v_and_b32_e32 v3, 24, v3
	v_and_b32_e32 v5, 4, v5
	s_addc_u32 s43, s26, s6
	s_add_i32 s54, s51, 0
	v_bfe_i32 v18, v2, 0, 16
	v_or3_b32 v3, v6, v5, v3
	s_add_i32 m0, s54, 0x10000
	v_add_u32_e32 v2, v17, v18
	v_mul_lo_u32 v3, s22, v3
	global_load_lds_dwordx4 v0, s[42:43]
	s_add_i32 m0, s54, 0x12000
	v_add_lshl_u32 v172, v3, v2, 1
	s_add_u32 s6, s42, s16
	global_load_lds_dwordx4 v172, s[42:43]
	s_addc_u32 s7, s43, 0
	s_add_i32 m0, s54, 0x14000
	s_mul_i32 s11, s50, s29
	global_load_lds_dwordx4 v0, s[6:7]
	s_add_i32 m0, s54, 0x16000
	s_mul_hi_i32 s10, s50, s29
	s_add_u32 s40, s52, s11
	v_mov_b32_e32 v173, v1
	s_addc_u32 s41, s53, s10
	s_add_i32 s55, s54, 0x2000
	v_mul_lo_u32 v19, s22, v4
	v_lshl_add_u64 v[6:7], s[6:7], 0, v[0:1]
	v_lshl_add_u64 v[8:9], s[6:7], 0, v[172:173]
	global_load_lds_dwordx4 v172, s[6:7]
	s_mov_b32 m0, s54
	s_add_u32 s6, s40, s16
	v_add_lshl_u32 v164, v19, v2, 1
	global_load_lds_dwordx4 v162, s[40:41]
	s_mov_b32 m0, s55
	s_addc_u32 s7, s41, 0
	s_add_i32 s58, s54, 0x4000
	global_load_lds_dwordx4 v164, s[40:41]
	s_mov_b32 m0, s58
	s_add_i32 s59, s54, 0x6000
	global_load_lds_dwordx4 v162, s[6:7]
	s_mov_b32 m0, s59
	v_mov_b32_e32 v163, v1
	global_load_lds_dwordx4 v164, s[6:7]
	v_mov_b32_e32 v165, v1
	s_cmp_eq_u32 s31, 1
	s_mov_b64 s[78:79], s[68:69]
	v_lshl_add_u64 v[2:3], s[42:43], 0, v[0:1]
	v_lshl_add_u64 v[4:5], s[42:43], 0, v[172:173]
	v_lshl_add_u64 v[10:11], s[40:41], 0, v[162:163]
	v_lshl_add_u64 v[12:13], s[40:41], 0, v[164:165]
	s_cselect_b64 s[6:7], -1, 0
	s_add_i32 m0, s54, 0x18000
	v_lshl_add_u64 v[2:3], v[2:3], 0, s[14:15]
	global_load_lds_dwordx4 v[2:3], off
	v_lshl_add_u64 v[2:3], v[4:5], 0, s[14:15]
	s_add_i32 m0, s54, 0x1a000
	s_add_i32 s65, s54, 0x8000
	global_load_lds_dwordx4 v[2:3], off
	v_lshl_add_u64 v[2:3], v[10:11], 0, s[14:15]
	s_mov_b32 m0, s65
	s_add_i32 s66, s54, 0xa000
	global_load_lds_dwordx4 v[2:3], off
	v_lshl_add_u64 v[2:3], v[12:13], 0, s[14:15]
	s_mov_b32 m0, s66
	s_nop 0
	global_load_lds_dwordx4 v[2:3], off
	s_add_i32 m0, s54, 0x1c000
	v_lshl_add_u64 v[2:3], v[6:7], 0, s[14:15]
	global_load_lds_dwordx4 v[2:3], off
	v_lshl_add_u64 v[2:3], v[8:9], 0, s[14:15]
	s_add_i32 m0, s54, 0x1e000
	s_nop 0
	global_load_lds_dwordx4 v[2:3], off
	s_cmp_lg_u32 s31, 1
	s_cbranch_scc1 .LBB0_364
	s_barrier
.LBB0_364:
	v_readlane_b32 s18, v254, 31
	s_cmp_eq_u32 s18, 3
	s_cselect_b64 s[10:11], -1, 0
	s_and_b64 s[8:9], s[10:11], s[8:9]
	s_and_b64 s[8:9], s[8:9], exec
	v_readlane_b32 s8, v254, 29
	v_readlane_b32 s9, v254, 30
	s_cselect_b32 s9, s9, 0
	s_cselect_b32 s8, s8, 0
	s_add_u32 s10, s36, 0xab00000
	s_addc_u32 s11, s37, 0
	s_lshl_b32 s34, s18, 1
	s_add_i32 s23, s34, s23
	s_add_i32 s23, s23, -1
	s_mul_hi_u32 s34, s23, 0x108000
	s_mul_i32 s23, s23, 0x108000
	v_readlane_b32 s18, v254, 36
	s_add_u32 s61, s18, s23
	v_readlane_b32 s18, v254, 39
	s_addc_u32 s62, s18, s34
	s_waitcnt vmcnt(8)
	s_barrier
	v_bfe_u32 v20, v170, 4, 2
	v_and_b32_e32 v21, 15, v170
	v_and_b32_e32 v3, 64, v206
	v_lshlrev_b32_e32 v23, 4, v20
	v_xor_b32_e32 v2, 16, v206
	v_add_u32_e32 v3, 64, v3
	v_lshl_or_b32 v171, s31, 6, v21
	v_lshl_or_b32 v21, v21, 6, v23
	v_lshlrev_b32_e32 v23, 2, v170
	v_cmp_lt_i32_e32 vcc, v2, v3
	s_and_b32 s63, s30, 3
	s_lshr_b32 s64, s22, 6
	s_lshl_b32 s22, s31, 13
	v_and_b32_e32 v23, 32, v23
	v_cndmask_b32_e32 v2, v206, v2, vcc
	v_bitop3_b32 v24, v21, s22, v23 bitop3:0xde
	s_lshl_b32 s22, s63, 12
	s_add_i32 s67, s64, -2
	v_lshlrev_b32_e32 v198, 2, v2
	v_xor_b32_e32 v2, 32, v206
	s_cmpk_lt_u32 s5, 0x100
	v_cmp_lt_i32_e32 vcc, v2, v3
	v_bitop3_b32 v196, s22, v21, v23 bitop3:0xf6
	s_cselect_b64 s[22:23], -1, 0
	s_ashr_i32 s5, s90, 31
	v_cndmask_b32_e32 v2, v206, v2, vcc
	s_and_b64 s[2:3], s[2:3], exec
	v_lshlrev_b32_e32 v199, 2, v2
	v_add_u32_e32 v2, v16, v14
	s_cselect_b32 s68, 0, s5
	s_cselect_b32 s69, 0x80, s90
	s_ashr_i32 s70, s20, 31
	s_lshr_b32 s71, s12, 1
	v_add_lshl_u32 v2, v2, v15, 1
	v_mov_b32_e32 v3, v1
	s_waitcnt vmcnt(6)
	s_cmp_eq_u64 s[8:9], 0
	v_lshl_add_u64 v[174:175], s[16:17], 0, v[2:3]
	v_add_u32_e32 v2, v19, v17
	v_lshlrev_b32_e32 v22, 3, v20
	s_cselect_b64 s[30:31], -1, 0
	s_cmp_lg_u64 s[8:9], 0
	v_add_lshl_u32 v2, v2, v18, 1
	s_mov_b32 s60, 0
	v_lshl_or_b32 v197, s63, 5, v22
	v_cmp_eq_u32_e64 s[36:37], 0, v20
	s_mov_b32 s5, s17
	s_cselect_b64 s[44:45], -1, 0
	v_lshl_add_u64 v[176:177], s[16:17], 0, v[2:3]
	v_add_u32_e32 v200, 0, v24
	s_barrier
	s_branch .LBB0_367

.LBB0_487:
	s_andn2_b64 vcc, exec, s[10:11]
	s_cbranch_vccnz .LBB0_614
	v_ashrrev_i32_e32 v2, 31, v170
	v_lshrrev_b32_e32 v2, 26, v2
	v_add_u32_e32 v2, v170, v2
	v_ashrrev_i32_e32 v10, 6, v2
	v_bfe_i32 v2, v170, 27, 1
	v_lshlrev_b32_e32 v0, 4, v170
	v_lshrrev_b32_e32 v2, 22, v2
	v_add_u32_e32 v2, v0, v2
	v_and_b32_e32 v2, 0xfffffc00, v2
	v_sub_u32_e32 v2, v0, v2
	v_lshrrev_b32_e32 v3, 4, v2
	v_bitop3_b32 v2, v3, v2, 32 bitop3:0x6c
	v_ashrrev_i32_e32 v4, 31, v2
	v_lshrrev_b32_e32 v4, 26, v4
	v_add_u32_e32 v4, v2, v4
	v_lshlrev_b32_e32 v3, 3, v10
	v_ashrrev_i32_e32 v11, 6, v4
	v_and_b32_e32 v4, 0xc0, v4
	v_and_b32_e32 v3, -16, v3
	v_sub_u32_e32 v2, v2, v4
	v_add_u32_e32 v3, v11, v3
	v_ashrrev_i16_sdwa v2, v209, sext(v2) dst_sel:DWORD dst_unused:UNUSED_PAD src0_sel:DWORD src1_sel:BYTE_0
	v_lshlrev_b32_e32 v5, 5, v10
	v_bfe_i32 v12, v2, 0, 16
	v_lshlrev_b32_e32 v2, 1, v3
	v_lshrrev_b32_e32 v4, 2, v3
	v_and_b32_e32 v6, 3, v11
	s_mov_b32 s58, 0x1fffe0
	v_and_b32_e32 v5, 32, v5
	v_and_b32_e32 v2, 24, v2
	v_and_b32_e32 v4, 4, v4
	v_and_or_b32 v6, v3, s58, v6
	v_or3_b32 v2, v6, v4, v2
	v_add_lshl_u32 v4, v5, v12, 1
	v_add_u32_e32 v0, 0x2000, v0
	v_lshl_add_u32 v152, v2, 11, v4
	v_ashrrev_i32_e32 v2, 31, v0
	v_lshrrev_b32_e32 v2, 22, v2
	v_add_u32_e32 v2, v0, v2
	v_ashrrev_i32_e32 v13, 10, v2
	v_mul_i32_i24_e32 v2, 0x400, v13
	v_sub_u32_e32 v0, v0, v2
	v_lshrrev_b32_e32 v2, 4, v0
	v_bitop3_b32 v0, v2, v0, 32 bitop3:0x6c
	v_lshl_add_u32 v150, v3, 11, v4
	v_ashrrev_i32_e32 v3, 31, v0
	v_lshrrev_b32_e32 v3, 26, v3
	v_lshlrev_b32_e32 v2, 3, v13
	v_add_u32_e32 v3, v0, v3
	v_and_b32_e32 v2, -16, v2
	v_ashrrev_i32_e32 v14, 6, v3
	v_add_u32_e32 v2, v14, v2
	v_and_b32_e32 v5, 3, v14
	v_and_or_b32 v5, v2, s58, v5
	v_and_b32_e32 v3, 0xc0, v3
	v_sub_u32_e32 v0, v0, v3
	v_ashrrev_i16_sdwa v0, v209, sext(v0) dst_sel:DWORD dst_unused:UNUSED_PAD src0_sel:DWORD src1_sel:BYTE_0
	v_lshlrev_b32_e32 v4, 5, v13
	v_bfe_i32 v15, v0, 0, 16
	v_lshlrev_b32_e32 v0, 1, v2
	v_lshrrev_b32_e32 v3, 2, v2
	v_and_b32_e32 v4, 32, v4
	v_and_b32_e32 v0, 24, v0
	v_and_b32_e32 v3, 4, v3
	v_or3_b32 v0, v5, v3, v0
	v_add_lshl_u32 v3, v4, v15, 1
	v_lshl_add_u32 v156, v0, 11, v3
	v_lshl_add_u32 v154, v2, 11, v3
	s_ashr_i32 s58, s16, 6
	s_lshl_b32 s52, s58, 10
	v_readlane_b32 s60, v254, 37
	v_readlane_b32 s61, v254, 38
	s_mul_i32 s62, s24, 0x300000
	s_add_u32 s62, s60, s62
	s_addc_u32 s63, s61, 0
	s_add_u32 s62, s62, 0xf00000
	s_addc_u32 s63, s63, 0
	s_mov_b32 s66, s2
	s_ashr_i32 s67, s2, 31
	s_lshl_b64 s[66:67], s[66:67], 19
	s_add_u32 s46, s62, s66
	s_addc_u32 s47, s63, s67
	s_mov_b32 s66, s42
	s_ashr_i32 s67, s42, 31
	s_lshl_b64 s[66:67], s[66:67], 19
	s_add_u32 s44, s60, 0xab00000
	s_addc_u32 s45, s61, 0
	s_add_u32 s44, s44, s66
	s_addc_u32 s45, s45, s67
	s_add_i32 m0, s52, 0x10000
	s_nop 0
	global_load_lds_dwordx4 v152, s[46:47]
	s_add_i32 m0, s52, 0x12000
	s_nop 0
	global_load_lds_dwordx4 v156, s[46:47]
	s_add_u32 s66, s46, 0x40000
	s_addc_u32 s67, s47, 0
	s_add_i32 m0, s52, 0x14000
	s_nop 0
	global_load_lds_dwordx4 v152, s[66:67]
	s_add_i32 m0, s52, 0x16000
	s_nop 0
	global_load_lds_dwordx4 v156, s[66:67]
	s_mov_b32 m0, s52
	s_nop 0
	global_load_lds_dwordx4 v150, s[44:45]
	s_add_i32 m0, s52, 0x2000
	s_nop 0
	global_load_lds_dwordx4 v154, s[44:45]
	s_add_u32 s66, s44, 0x40000
	s_addc_u32 s67, s45, 0
	s_add_i32 m0, s52, 0x4000
	s_nop 0
	global_load_lds_dwordx4 v150, s[66:67]
	s_add_i32 m0, s52, 0x6000
	s_nop 0
	global_load_lds_dwordx4 v154, s[66:67]
	s_add_u32 s66, s46, 0x80
	s_addc_u32 s67, s47, 0
	s_add_i32 m0, s52, 0x18000
	s_nop 0
	global_load_lds_dwordx4 v152, s[66:67]
	s_add_i32 m0, s52, 0x1a000
	s_nop 0
	global_load_lds_dwordx4 v156, s[66:67]
	s_add_u32 s66, s44, 0x80
	s_addc_u32 s67, s45, 0
	s_add_i32 m0, s52, 0x8000
	s_nop 0
	global_load_lds_dwordx4 v150, s[66:67]
	s_add_i32 m0, s52, 0xa000
	s_nop 0
	global_load_lds_dwordx4 v154, s[66:67]
	s_add_u32 s66, s46, 0x40080
	s_addc_u32 s67, s47, 0
	s_add_i32 m0, s52, 0x1c000
	s_nop 0
	global_load_lds_dwordx4 v152, s[66:67]
	s_add_i32 m0, s52, 0x1e000
	s_nop 0
	global_load_lds_dwordx4 v156, s[66:67]
	v_ashrrev_i32_e32 v2, 8, v170
	s_ashr_i32 s95, s94, 31
	v_cmp_gt_i32_e32 vcc, 8, v2
	s_and_saveexec_b64 s[10:11], vcc
	s_cbranch_execz .LBB0_499
	v_and_b32_e32 v0, 0xff, v170
	s_waitcnt lgkmcnt(0)
	v_lshlrev_b32_e32 v3, 2, v0
	v_add_u32_e32 v6, -2, v2
	v_lshl_or_b32 v3, v2, 10, v3
	v_readlane_b32 s3, v254, 19
	v_mul_lo_u32 v2, s90, v2
	s_ashr_i32 s91, s90, 31
	v_add_u32_e32 v8, s3, v3
	v_add_u32_e32 v7, s94, v2
	v_mov_b64_e32 v[2:3], s[94:95]
	s_lshl_b32 s3, s90, 1
	v_mad_i64_i32 v[2:3], s[20:21], v6, s90, v[2:3]
	s_lshl_b64 s[22:23], s[90:91], 1
	s_mov_b64 s[30:31], 0
	s_branch .LBB0_492

.LBB0_501:
	s_lshl_b32 s3, s24, 10
	v_readlane_b32 s30, v254, 37
	v_readlane_b32 s31, v254, 38
	s_add_u32 s22, s30, s3
	s_addc_u32 s23, s31, 0
	s_and_b32 s3, s8, 3
	s_add_i32 m0, s52, 0x18000
	v_lshl_add_u64 v[8:9], v[8:9], 0, s[14:15]
	s_lshl_b32 s58, s9, 6
	s_lshl_b32 s10, s9, 13
	s_lshl_b32 s11, s3, 12
	s_waitcnt vmcnt(2)
	s_barrier
	v_lshl_add_u64 v[6:7], v[6:7], 0, s[14:15]
	s_add_i32 m0, s52, 0x1a000
	s_add_i32 s59, s52, 0x8000
	s_add_i32 s60, s52, 0xa000
	v_lshl_add_u64 v[4:5], v[4:5], 0, s[14:15]
	s_mov_b32 m0, s59
	s_add_u32 s8, s46, 0x40080
	v_lshl_add_u64 v[2:3], v[2:3], 0, s[14:15]
	s_mov_b32 m0, s60
	s_addc_u32 s9, s47, 0
	s_add_i32 m0, s52, 0x1c000
	v_lshl_add_u64 v[2:3], s[8:9], 0, v[152:153]
	v_lshl_add_u64 v[2:3], s[8:9], 0, v[156:157]
	s_add_i32 m0, s52, 0x1e000
	v_lshrrev_b32_e32 v0, 1, v170
	v_and_b32_e32 v171, 15, v170
	v_and_b32_e32 v0, 24, v0
	v_lshlrev_b32_e32 v2, 1, v0
	v_lshlrev_b32_e32 v4, 2, v171
	v_lshl_or_b32 v3, v171, 6, v2
	v_and_b32_e32 v5, 32, v4
	s_cmpk_lt_u32 s16, 0x100
	v_bitop3_b32 v6, v3, s10, v5 bitop3:0xde
	s_cselect_b64 s[8:9], -1, 0
	s_and_b32 s10, s16, 0xffffff00
	s_add_i32 s10, s10, 0
	s_add_i32 s10, s10, 0x20800
	v_add_u32_e32 v199, s10, v4
	s_lshl_b32 s10, s3, 6
	s_ashr_i32 s61, s90, 31
	v_lshlrev_b32_e32 v0, 2, v0
	s_lshl_b32 s3, s3, 7
	v_bitop3_b32 v198, s11, v3, v5 bitop3:0xf6
	v_mov_b32_e32 v3, 0xfff80000
	v_lshl_add_u64 v[4:5], s[22:23], 0, v[0:1]
	s_mov_b64 s[18:19], 0x108000
	s_add_u32 s22, s30, s3
	v_and_or_b32 v200, v170, 3, v3
	v_lshl_add_u64 v[158:159], v[4:5], 0, s[18:19]
	s_addc_u32 s23, s31, 0
	v_mov_b32_e32 v3, v1
	v_readlane_b32 s18, v254, 29
	v_lshl_add_u64 v[160:161], s[22:23], 0, v[2:3]
	v_readlane_b32 s19, v254, 30
	v_and_b32_e32 v2, 64, v206
	v_add_u32_e32 v2, 64, v2
	v_lshl_add_u64 v[162:163], s[18:19], 0, v[0:1]
	v_xor_b32_e32 v0, 16, v206
	v_cmp_lt_i32_e32 vcc, v0, v2
	s_waitcnt vmcnt(6)
	s_mov_b32 s11, s17
	s_lshl_b32 s62, s24, 22
	v_cndmask_b32_e32 v0, v206, v0, vcc
	v_lshlrev_b32_e32 v201, 2, v0
	v_xor_b32_e32 v0, 32, v206
	v_cmp_lt_i32_e32 vcc, v0, v2
	v_and_b32_e32 v2, 1, v10
	s_lshl_b32 s63, s24, 17
	v_cndmask_b32_e32 v0, v206, v0, vcc
	v_lshlrev_b32_e32 v202, 2, v0
	v_lshlrev_b32_e32 v0, 14, v10
	v_and_b32_e32 v0, 0xffff8000, v0
	v_lshl_add_u32 v0, v11, 11, v0
	v_lshl_or_b32 v0, v2, 6, v0
	v_lshl_add_u32 v164, v12, 1, v0
	v_lshlrev_b32_e32 v0, 14, v13
	v_and_b32_e32 v0, 0xffff8000, v0
	v_lshl_add_u32 v0, v14, 11, v0
	v_and_b32_e32 v2, 1, v13
	v_lshl_or_b32 v0, v2, 6, v0
	v_mov_b32_e32 v165, v1
	v_lshl_add_u32 v172, v15, 1, v0
	v_mov_b32_e32 v173, v1
	s_mov_b32 s3, 0
	v_add_u32_e32 v203, 0, v6
	s_barrier
	s_branch .LBB0_504

.LBB0_929:
	v_ashrrev_i32_e32 v0, 31, v170
	v_lshrrev_b32_e32 v0, 26, v0
	v_add_u32_e32 v0, v170, v0
	s_waitcnt vmcnt(0)
	v_ashrrev_i32_e32 v171, 6, v0
	v_bfe_i32 v0, v170, 27, 1
	v_lshlrev_b32_e32 v2, 4, v170
	v_lshrrev_b32_e32 v0, 22, v0
	v_add_u32_e32 v0, v2, v0
	v_and_b32_e32 v0, 0xfffffc00, v0
	v_sub_u32_e32 v0, v2, v0
	s_waitcnt lgkmcnt(0)
	v_lshrrev_b32_e32 v3, 4, v0
	v_bitop3_b32 v0, v3, v0, 32 bitop3:0x6c
	v_ashrrev_i32_e32 v4, 31, v0
	v_lshrrev_b32_e32 v4, 26, v4
	v_add_u32_e32 v4, v0, v4
	v_lshlrev_b32_e32 v3, 3, v171
	v_ashrrev_i32_e32 v173, 6, v4
	v_and_b32_e32 v4, 0xc0, v4
	v_and_b32_e32 v3, -16, v3
	v_sub_u32_e32 v0, v0, v4
	v_add_u32_e32 v3, v173, v3
	v_ashrrev_i16_sdwa v0, v209, sext(v0) dst_sel:DWORD dst_unused:UNUSED_PAD src0_sel:DWORD src1_sel:BYTE_0
	v_lshlrev_b32_e32 v5, 5, v171
	v_bfe_i32 v214, v0, 0, 16
	v_lshlrev_b32_e32 v0, 1, v3
	v_lshrrev_b32_e32 v4, 2, v3
	v_and_b32_e32 v6, 3, v173
	s_mov_b32 s8, 0x1fffe0
	v_and_b32_e32 v5, 32, v5
	v_and_b32_e32 v0, 24, v0
	v_and_b32_e32 v4, 4, v4
	v_and_or_b32 v6, v3, s8, v6
	v_or3_b32 v0, v6, v4, v0
	v_add_lshl_u32 v4, v5, v214, 1
	v_add_u32_e32 v2, 0x2000, v2
	v_lshl_add_u32 v150, v3, 11, v4
	v_ashrrev_i32_e32 v3, 31, v2
	v_lshrrev_b32_e32 v3, 22, v3
	v_add_u32_e32 v3, v2, v3
	v_ashrrev_i32_e32 v215, 10, v3
	v_mul_i32_i24_e32 v3, 0x400, v215
	v_sub_u32_e32 v2, v2, v3
	v_lshrrev_b32_e32 v3, 4, v2
	v_bitop3_b32 v2, v3, v2, 32 bitop3:0x6c
	v_lshl_add_u32 v0, v0, 11, v4
	v_ashrrev_i32_e32 v4, 31, v2
	v_lshrrev_b32_e32 v4, 26, v4
	v_add_u32_e32 v4, v2, v4
	v_lshlrev_b32_e32 v3, 3, v215
	v_ashrrev_i32_e32 v216, 6, v4
	v_and_b32_e32 v4, 0xc0, v4
	v_and_b32_e32 v3, -16, v3
	v_sub_u32_e32 v2, v2, v4
	v_add_u32_e32 v3, v216, v3
	v_ashrrev_i16_sdwa v2, v209, sext(v2) dst_sel:DWORD dst_unused:UNUSED_PAD src0_sel:DWORD src1_sel:BYTE_0
	v_lshlrev_b32_e32 v5, 5, v215
	v_bfe_i32 v217, v2, 0, 16
	v_lshlrev_b32_e32 v2, 1, v3
	v_lshrrev_b32_e32 v4, 2, v3
	v_and_b32_e32 v6, 3, v216
	v_and_b32_e32 v5, 32, v5
	v_and_b32_e32 v2, 24, v2
	v_and_b32_e32 v4, 4, v4
	v_and_or_b32 v6, v3, s8, v6
	v_or3_b32 v2, v6, v4, v2
	v_add_lshl_u32 v4, v5, v217, 1
	v_lshl_add_u32 v154, v2, 11, v4
	v_lshrrev_b32_e32 v2, 1, v170
	v_lshl_add_u32 v152, v3, 11, v4
	v_and_b32_e32 v219, 15, v170
	v_and_b32_e32 v218, 24, v2
	v_lshlrev_b32_e32 v3, 2, v170
	v_lshlrev_b32_e32 v156, 1, v218
	v_lshlrev_b32_e32 v2, 6, v219
	v_and_b32_e32 v3, 32, v3
	s_andn2_b64 vcc, exec, s[6:7]
	v_bitop3_b32 v220, v156, v3, v2 bitop3:0x36
	s_cbranch_vccnz .LBB0_1271
	s_ashr_i32 s59, s20, 6
	s_lshl_b32 s55, s59, 10
	s_mul_i32 s60, s24, 0x680000
	s_add_u32 s60, s70, s60
	s_addc_u32 s61, s71, 0
	s_add_u32 s53, s60, 0x200000
	s_addc_u32 s54, s61, 0
	s_ashr_i32 s39, s38, 31
	s_lshl_b64 s[60:61], s[38:39], 19
	s_add_u32 s46, s53, s60
	s_addc_u32 s47, s54, s61
	s_ashr_i32 s43, s42, 31
	s_lshl_b64 s[60:61], s[42:43], 19
	s_add_u32 s44, s70, 0xab00000
	s_addc_u32 s45, s71, 0
	s_add_u32 s44, s44, s60
	s_addc_u32 s45, s45, s61
	s_add_i32 m0, s55, 0x10000
	s_nop 0
	global_load_lds_dwordx4 v0, s[46:47]
	s_add_i32 m0, s55, 0x12000
	s_nop 0
	global_load_lds_dwordx4 v154, s[46:47]
	s_add_u32 s60, s46, 0x40000
	s_addc_u32 s61, s47, 0
	s_add_i32 m0, s55, 0x14000
	s_nop 0
	global_load_lds_dwordx4 v0, s[60:61]
	s_add_i32 m0, s55, 0x16000
	s_nop 0
	global_load_lds_dwordx4 v154, s[60:61]
	s_mov_b32 m0, s55
	s_nop 0
	global_load_lds_dwordx4 v150, s[44:45]
	s_add_i32 m0, s55, 0x2000
	s_nop 0
	global_load_lds_dwordx4 v152, s[44:45]
	s_add_u32 s60, s44, 0x40000
	s_addc_u32 s61, s45, 0
	s_add_i32 m0, s55, 0x4000
	s_nop 0
	global_load_lds_dwordx4 v150, s[60:61]
	s_add_i32 m0, s55, 0x6000
	s_nop 0
	global_load_lds_dwordx4 v152, s[60:61]
	s_add_u32 s60, s46, 0x80
	s_addc_u32 s61, s47, 0
	s_add_i32 m0, s55, 0x18000
	s_nop 0
	global_load_lds_dwordx4 v0, s[60:61]
	s_add_i32 m0, s55, 0x1a000
	s_nop 0
	global_load_lds_dwordx4 v154, s[60:61]
	s_add_u32 s60, s44, 0x80
	s_addc_u32 s61, s45, 0
	s_add_i32 m0, s55, 0x8000
	s_nop 0
	global_load_lds_dwordx4 v150, s[60:61]
	s_add_i32 m0, s55, 0xa000
	s_nop 0
	global_load_lds_dwordx4 v152, s[60:61]
	s_add_u32 s60, s46, 0x40080
	s_addc_u32 s61, s47, 0
	s_add_i32 m0, s55, 0x1c000
	s_nop 0
	global_load_lds_dwordx4 v0, s[60:61]
	s_add_i32 m0, s55, 0x1e000
	s_nop 0
	global_load_lds_dwordx4 v154, s[60:61]
	v_ashrrev_i32_e32 v2, 8, v170
	s_ashr_i32 s95, s94, 31
	v_cmp_gt_i32_e32 vcc, 8, v2
	s_and_saveexec_b64 s[6:7], vcc
	s_cbranch_execz .LBB0_1055
	v_and_b32_e32 v6, 0xff, v170
	v_lshlrev_b32_e32 v3, 2, v6
	v_add_u32_e32 v7, -2, v2
	v_lshl_or_b32 v3, v2, 10, v3
	v_readlane_b32 s8, v254, 19
	v_mul_lo_u32 v2, s90, v2
	v_add_u32_e32 v8, s94, v2
	v_add_u32_e32 v9, s8, v3
	v_mov_b64_e32 v[2:3], s[94:95]
	s_ashr_i32 s91, s90, 31
	v_mad_i64_i32 v[2:3], s[8:9], v7, s90, v[2:3]
	s_lshl_b32 s13, s90, 1
	s_lshl_b64 s[8:9], s[90:91], 1
	s_mov_b64 s[10:11], 0
	s_branch .LBB0_934

.LBB0_1057:
	s_lshl_b32 s6, s24, 13
	s_add_u32 s6, s70, s6
	s_addc_u32 s7, s71, 0
	s_add_u32 s6, s6, 0x100000
	s_addc_u32 s7, s7, 0
	s_add_u32 s59, s70, 0xf600000
	s_addc_u32 s60, s71, 0
	s_add_i32 m0, s55, 0x18000
	v_lshl_add_u64 v[8:9], v[8:9], 0, s[14:15]
	s_and_b32 s22, s9, 3
	s_lshl_b32 s9, s8, 13
	s_waitcnt vmcnt(2)
	s_barrier
	v_lshl_add_u64 v[6:7], v[6:7], 0, s[14:15]
	s_add_i32 m0, s55, 0x1a000
	s_add_i32 s61, s55, 0x8000
	s_add_i32 s62, s55, 0xa000
	v_lshl_add_u64 v[4:5], v[4:5], 0, s[14:15]
	s_mov_b32 m0, s61
	s_add_u32 s10, s46, 0x40080
	v_lshl_add_u64 v[2:3], v[2:3], 0, s[14:15]
	s_mov_b32 m0, s62
	s_addc_u32 s11, s47, 0
	s_add_i32 m0, s55, 0x1c000
	v_lshl_add_u64 v[2:3], s[10:11], 0, v[0:1]
	v_lshl_add_u64 v[2:3], s[10:11], 0, v[154:155]
	s_add_i32 m0, s55, 0x1e000
	s_cmpk_lt_u32 s20, 0x100
	v_lshlrev_b32_e32 v3, 2, v219
	v_lshl_or_b32 v2, v219, 6, v156
	v_and_b32_e32 v4, 32, v3
	v_lshl_or_b32 v221, s8, 6, v219
	v_bitop3_b32 v4, v2, s9, v4 bitop3:0xde
	s_cselect_b64 s[8:9], -1, 0
	s_and_b32 s10, s20, 0xffffff00
	s_add_i32 s10, s10, 0
	s_add_i32 s10, s10, 0x20800
	v_add_u32_e32 v223, s10, v3
	v_lshlrev_b32_e32 v2, 2, v218
	v_mov_b32_e32 v3, v1
	v_lshl_add_u64 v[2:3], s[6:7], 0, v[2:3]
	s_mov_b64 s[20:21], 0x1800
	v_lshl_add_u64 v[158:159], v[2:3], 0, s[20:21]
	v_and_b32_e32 v3, 64, v206
	v_xor_b32_e32 v2, 16, v206
	v_add_u32_e32 v3, 64, v3
	v_cmp_lt_i32_e32 vcc, v2, v3
	s_ashr_i32 s63, s90, 31
	s_lshl_b32 s10, s22, 7
	v_cndmask_b32_e32 v2, v206, v2, vcc
	v_lshlrev_b32_e32 v224, 2, v2
	v_xor_b32_e32 v2, 32, v206
	s_add_u32 s18, s70, s10
	v_cmp_lt_i32_e32 vcc, v2, v3
	s_addc_u32 s19, s71, 0
	v_mov_b32_e32 v157, v1
	v_cndmask_b32_e32 v2, v206, v2, vcc
	v_lshlrev_b32_e32 v225, 2, v2
	v_lshl_add_u64 v[2:3], s[18:19], 0, v[156:157]
	s_mov_b64 s[18:19], 0xed00000
	v_lshl_add_u64 v[160:161], v[2:3], 0, s[18:19]
	v_lshlrev_b32_e32 v2, 14, v171
	v_and_b32_e32 v2, 0xffff8000, v2
	v_lshl_add_u32 v2, v173, 11, v2
	v_and_b32_e32 v3, 1, v171
	v_lshl_or_b32 v2, v3, 6, v2
	v_lshl_add_u32 v162, v214, 1, v2
	v_lshlrev_b32_e32 v2, 14, v215
	v_and_b32_e32 v2, 0xffff8000, v2
	s_waitcnt vmcnt(6)
	v_lshl_add_u32 v2, v216, 11, v2
	v_and_b32_e32 v3, 1, v215
	s_add_u32 s10, s70, 0x15900000
	v_lshl_or_b32 v2, v3, 6, v2
	v_lshl_or_b32 v222, s22, 12, v220
	s_addc_u32 s11, s71, 0
	v_lshl_or_b32 v226, s22, 5, v218
	v_mov_b32_e32 v163, v1
	v_lshl_add_u32 v164, v217, 1, v2
	v_mov_b32_e32 v165, v1
	s_mov_b32 s20, 0
	v_add_u32_e32 v157, 0, v4
	s_barrier
	s_branch .LBB0_1060
